# speedup vs baseline: 1.0103x; 1.0103x over previous
.LBB0_55:
	s_or_b64 s[6:7], s[16:17], s[6:7]
	v_mov_b32_e32 v232, 0
	s_and_b64 vcc, exec, s[6:7]
	v_mov_b32_e32 v225, 0
	v_mov_b32_e32 v226, 0
	v_mov_b32_e32 v227, 0
	v_mov_b32_e32 v228, 0
	v_mov_b32_e32 v229, 0
	v_mov_b32_e32 v230, 0
	v_mov_b32_e32 v231, 0
	v_mov_b32_e32 v224, 0
	v_mov_b32_e32 v218, 0
	v_mov_b32_e32 v219, 0
	v_mov_b32_e32 v220, 0
	v_mov_b32_e32 v221, 0
	v_mov_b32_e32 v222, 0
	v_mov_b32_e32 v223, 0
	v_mov_b32_e32 v233, 0
	s_cbranch_vccnz .LBB0_57
	s_load_dwordx2 s[6:7], s[0:1], 0xe8
	s_ashr_i32 s27, s26, 31
	v_ashrrev_i32_e32 v148, 4, v217
	s_lshl_b64 s[8:9], s[26:27], 2
	v_and_b32_e32 v128, -16, v148
	s_waitcnt lgkmcnt(0)
	s_add_u32 s6, s6, s8
	s_addc_u32 s7, s7, s9
	v_lshlrev_b32_sdwa v192, v213, v217 dst_sel:DWORD dst_unused:UNUSED_PAD src0_sel:DWORD src1_sel:BYTE_0
	v_ashrrev_i32_e32 v129, 31, v128
	v_or_b32_e32 v134, 1, v128
	v_or_b32_e32 v136, 2, v128
	v_or_b32_e32 v138, 3, v128
	v_or_b32_e32 v140, 4, v128
	v_or_b32_e32 v142, 5, v128
	v_or_b32_e32 v144, 6, v128
	v_or_b32_e32 v146, 7, v128
	v_lshl_add_u64 v[130:131], s[6:7], 0, v[192:193]
	v_lshlrev_b64 v[132:133], 16, v[128:129]
	v_ashrrev_i32_e32 v135, 31, v134
	v_ashrrev_i32_e32 v137, 31, v136
	v_ashrrev_i32_e32 v139, 31, v138
	v_ashrrev_i32_e32 v141, 31, v140
	v_ashrrev_i32_e32 v143, 31, v142
	v_ashrrev_i32_e32 v145, 31, v144
	v_ashrrev_i32_e32 v147, 31, v146
	v_lshl_add_u64 v[132:133], v[130:131], 0, v[132:133]
	v_lshlrev_b64 v[134:135], 16, v[134:135]
	v_lshlrev_b64 v[136:137], 16, v[136:137]
	v_lshlrev_b64 v[138:139], 16, v[138:139]
	v_lshlrev_b64 v[140:141], 16, v[140:141]
	v_lshlrev_b64 v[142:143], 16, v[142:143]
	v_lshlrev_b64 v[144:145], 16, v[144:145]
	v_lshlrev_b64 v[146:147], 16, v[146:147]
	v_lshl_add_u64 v[134:135], v[130:131], 0, v[134:135]
	v_lshl_add_u64 v[136:137], v[130:131], 0, v[136:137]
	v_lshl_add_u64 v[138:139], v[130:131], 0, v[138:139]
	v_lshl_add_u64 v[140:141], v[130:131], 0, v[140:141]
	v_lshl_add_u64 v[142:143], v[130:131], 0, v[142:143]
	v_lshl_add_u64 v[144:145], v[130:131], 0, v[144:145]
	v_lshl_add_u64 v[146:147], v[130:131], 0, v[146:147]
	global_load_dword v233, v[132:133], off
	global_load_dword v223, v[134:135], off
	global_load_dword v222, v[136:137], off
	global_load_dword v221, v[138:139], off
	global_load_dword v220, v[140:141], off
	global_load_dword v219, v[142:143], off
	global_load_dword v218, v[144:145], off
	global_load_dword v224, v[146:147], off
	v_or_b32_e32 v132, 8, v128
	v_ashrrev_i32_e32 v133, 31, v132
	v_or_b32_e32 v134, 9, v128
	v_or_b32_e32 v136, 10, v128
	v_or_b32_e32 v138, 11, v128
	v_or_b32_e32 v140, 12, v128
	v_or_b32_e32 v142, 13, v128
	v_or_b32_e32 v128, 14, v128
	v_or_b32_e32 v144, 15, v148
	v_lshlrev_b64 v[132:133], 16, v[132:133]
	v_ashrrev_i32_e32 v135, 31, v134
	v_ashrrev_i32_e32 v137, 31, v136
	v_ashrrev_i32_e32 v139, 31, v138
	v_ashrrev_i32_e32 v141, 31, v140
	v_ashrrev_i32_e32 v143, 31, v142
	v_ashrrev_i32_e32 v129, 31, v128
	v_ashrrev_i32_e32 v145, 31, v144
	v_lshl_add_u64 v[132:133], v[130:131], 0, v[132:133]
	v_lshlrev_b64 v[134:135], 16, v[134:135]
	v_lshlrev_b64 v[136:137], 16, v[136:137]
	v_lshlrev_b64 v[138:139], 16, v[138:139]
	v_lshlrev_b64 v[140:141], 16, v[140:141]
	v_lshlrev_b64 v[142:143], 16, v[142:143]
	v_lshlrev_b64 v[128:129], 16, v[128:129]
	v_lshlrev_b64 v[144:145], 16, v[144:145]
	v_lshl_add_u64 v[134:135], v[130:131], 0, v[134:135]
	v_lshl_add_u64 v[136:137], v[130:131], 0, v[136:137]
	v_lshl_add_u64 v[138:139], v[130:131], 0, v[138:139]
	v_lshl_add_u64 v[140:141], v[130:131], 0, v[140:141]
	v_lshl_add_u64 v[142:143], v[130:131], 0, v[142:143]
	v_lshl_add_u64 v[128:129], v[130:131], 0, v[128:129]
	v_lshl_add_u64 v[130:131], v[130:131], 0, v[144:145]
	global_load_dword v231, v[132:133], off
	global_load_dword v230, v[134:135], off
	global_load_dword v229, v[136:137], off
	global_load_dword v228, v[138:139], off
	global_load_dword v227, v[140:141], off
	global_load_dword v226, v[142:143], off
	global_load_dword v225, v[128:129], off
	global_load_dword v232, v[130:131], off

.LBB0_314:
	s_waitcnt vmcnt(0)
	v_add_f32_e32 v0, v223, v233
	v_add_f32_e32 v0, v222, v0
	v_add_f32_e32 v0, v221, v0
	v_add_f32_e32 v0, v220, v0
	v_add_f32_e32 v0, v219, v0
	v_add_f32_e32 v0, v218, v0
	v_add_f32_e32 v0, v224, v0
	v_add_f32_e32 v0, v231, v0
	v_add_f32_e32 v0, v230, v0
	s_lshl_b32 s6, s90, 9
	v_add_f32_e32 v0, v229, v0
	v_add_f32_e32 v0, v228, v0
	s_xor_b32 s6, s6, 0x200
	v_add_f32_e32 v0, v227, v0
	s_lshl_b32 s6, s6, 2
	v_add_f32_e32 v0, v226, v0
	s_add_i32 s6, s6, 0
	v_add_f32_e32 v0, v225, v0
	v_lshl_add_u32 v1, v217, 2, s6
	v_add_f32_e32 v0, v232, v0
	v_add_u32_e32 v1, 0x20000, v1
	ds_write_b32 v1, v0
	s_branch .LBB0_46
